# UP epilogue: silu chains batched per row block with packed f32 mul/add (fewer VALU instrs)
# speedup vs baseline: 1.0673x; 1.0031x over previous
.LBB0_652:
	v_lshl_add_u32 v142, v151, 2, s44
	ds_read2_b32 v[148:149], v142 offset1:16
	ds_read2_b32 v[146:147], v142 offset0:32 offset1:48
	ds_read2_b32 v[144:145], v142 offset0:64 offset1:80
	ds_read2_b32 v[142:143], v142 offset0:96 offset1:112
	v_add_u32_e32 v155, s4, v151
	s_waitcnt lgkmcnt(0)
	v_pk_mul_f32 v[126:127], v[126:127], v[148:149] op_sel_hi:[1,0]
	v_pk_mul_f32 v[122:123], v[122:123], v[148:149] op_sel_hi:[1,0]
	v_pk_mul_f32 v[118:119], v[118:119], v[148:149] op_sel_hi:[1,0]
	v_pk_mul_f32 v[114:115], v[114:115], v[148:149] op_sel_hi:[1,0]
	v_pk_mul_f32 v[128:129], v[128:129], v[148:149] op_sel_hi:[1,0]
	v_pk_mul_f32 v[124:125], v[124:125], v[148:149] op_sel_hi:[1,0]
	v_pk_mul_f32 v[120:121], v[120:121], v[148:149] op_sel_hi:[1,0]
	v_pk_mul_f32 v[116:117], v[116:117], v[148:149] op_sel_hi:[1,0]
	v_mov_b32_e32 v176, 0xbfb8aa3b
	v_pk_mul_f32 v[168:169], v[126:127], v[176:177] op_sel_hi:[1,0]
	v_pk_mul_f32 v[170:171], v[122:123], v[176:177] op_sel_hi:[1,0]
	v_pk_mul_f32 v[172:173], v[128:129], v[176:177] op_sel_hi:[1,0]
	v_pk_mul_f32 v[174:175], v[124:125], v[176:177] op_sel_hi:[1,0]
	v_exp_f32_e32 v168, v168
	v_exp_f32_e32 v169, v169
	v_exp_f32_e32 v170, v170
	v_exp_f32_e32 v171, v171
	v_exp_f32_e32 v172, v172
	v_exp_f32_e32 v173, v173
	v_exp_f32_e32 v174, v174
	v_exp_f32_e32 v175, v175
	v_pk_add_f32 v[168:169], v[168:169], 1.0 op_sel_hi:[1,0]
	v_pk_add_f32 v[170:171], v[170:171], 1.0 op_sel_hi:[1,0]
	v_pk_add_f32 v[172:173], v[172:173], 1.0 op_sel_hi:[1,0]
	v_pk_add_f32 v[174:175], v[174:175], 1.0 op_sel_hi:[1,0]
	v_rcp_f32_e32 v168, v168
	v_rcp_f32_e32 v169, v169
	v_rcp_f32_e32 v170, v170
	v_rcp_f32_e32 v171, v171
	v_rcp_f32_e32 v172, v172
	v_rcp_f32_e32 v173, v173
	v_rcp_f32_e32 v174, v174
	v_rcp_f32_e32 v175, v175
	v_pk_mul_f32 v[168:169], v[126:127], v[168:169]
	v_pk_mul_f32 v[170:171], v[122:123], v[170:171]
	v_pk_mul_f32 v[172:173], v[128:129], v[172:173]
	v_pk_mul_f32 v[174:175], v[124:125], v[174:175]
	v_pk_mul_f32 v[118:119], v[118:119], v[168:169]
	v_pk_mul_f32 v[114:115], v[114:115], v[170:171]
	v_pk_mul_f32 v[120:121], v[120:121], v[172:173]
	v_pk_mul_f32 v[116:117], v[116:117], v[174:175]
	s_lshl_b32 s0, s47, 7
	s_ashr_i32 s1, s0, 31
	v_add_u32_e32 v148, s50, v155
	s_movk_i32 s18, 0x1600
	v_lshlrev_b32_e32 v150, 3, v150
	s_lshl_b64 s[0:1], s[0:1], 1
	v_ashrrev_i32_e32 v151, 31, v150
	v_pk_mul_f32 v[94:95], v[94:95], v[146:147] op_sel_hi:[1,0]
	v_pk_mul_f32 v[90:91], v[90:91], v[146:147] op_sel_hi:[1,0]
	v_pk_mul_f32 v[86:87], v[86:87], v[146:147] op_sel_hi:[1,0]
	v_pk_mul_f32 v[82:83], v[82:83], v[146:147] op_sel_hi:[1,0]
	v_pk_mul_f32 v[96:97], v[96:97], v[146:147] op_sel_hi:[1,0]
	v_cvt_pk_bf16_f32 v118, v118, v119
	v_pk_mul_f32 v[92:93], v[92:93], v[146:147] op_sel_hi:[1,0]
	v_pk_mul_f32 v[88:89], v[88:89], v[146:147] op_sel_hi:[1,0]
	v_pk_mul_f32 v[84:85], v[84:85], v[146:147] op_sel_hi:[1,0]
	v_pk_mul_f32 v[62:63], v[62:63], v[144:145] op_sel_hi:[1,0]
	v_pk_mul_f32 v[58:59], v[58:59], v[144:145] op_sel_hi:[1,0]
	v_pk_mul_f32 v[54:55], v[54:55], v[144:145] op_sel_hi:[1,0]
	v_pk_mul_f32 v[50:51], v[50:51], v[144:145] op_sel_hi:[1,0]
	v_pk_mul_f32 v[64:65], v[64:65], v[144:145] op_sel_hi:[1,0]
	v_pk_mul_f32 v[60:61], v[60:61], v[144:145] op_sel_hi:[1,0]
	v_pk_mul_f32 v[56:57], v[56:57], v[144:145] op_sel_hi:[1,0]
	v_pk_mul_f32 v[52:53], v[52:53], v[144:145] op_sel_hi:[1,0]
	v_pk_mul_f32 v[30:31], v[30:31], v[142:143] op_sel_hi:[1,0]
	v_pk_mul_f32 v[26:27], v[26:27], v[142:143] op_sel_hi:[1,0]
	v_pk_mul_f32 v[22:23], v[22:23], v[142:143] op_sel_hi:[1,0]
	v_pk_mul_f32 v[18:19], v[18:19], v[142:143] op_sel_hi:[1,0]
	v_pk_mul_f32 v[32:33], v[32:33], v[142:143] op_sel_hi:[1,0]
	v_pk_mul_f32 v[28:29], v[28:29], v[142:143] op_sel_hi:[1,0]
	v_pk_mul_f32 v[24:25], v[24:25], v[142:143] op_sel_hi:[1,0]
	v_pk_mul_f32 v[20:21], v[20:21], v[142:143] op_sel_hi:[1,0]
	s_and_b64 vcc, exec, s[8:9]
	s_mov_b32 s47, s46
	s_mov_b32 s48, s45
	v_cvt_pk_bf16_f32 v119, v120, v121
	v_cvt_pk_bf16_f32 v120, v114, v115
	v_mov_b64_e32 v[114:115], s[2:3]
	v_cvt_pk_bf16_f32 v121, v116, v117
	v_mad_i64_i32 v[116:117], s[4:5], v148, s18, v[114:115]
	v_lshl_add_u64 v[116:117], v[116:117], 0, s[0:1]
	v_lshl_add_u64 v[122:123], v[116:117], 0, s[92:93]
	v_lshlrev_b64 v[116:117], 1, v[150:151]
	v_lshl_add_u64 v[122:123], v[122:123], 0, v[116:117]
	global_store_dwordx4 v[122:123], v[118:121], off nt
	s_nop 1
	v_mov_b32_e32 v118, v149
	v_pk_mul_f32 v[110:111], v[110:111], v[118:119] op_sel_hi:[1,0]
	v_pk_mul_f32 v[112:113], v[112:113], v[118:119] op_sel_hi:[1,0]
	v_pk_mul_f32 v[108:109], v[108:109], v[118:119] op_sel_hi:[1,0]
	v_pk_mul_f32 v[106:107], v[106:107], v[118:119] op_sel_hi:[1,0]
	v_pk_mul_f32 v[104:105], v[104:105], v[118:119] op_sel_hi:[1,0]
	v_pk_mul_f32 v[102:103], v[102:103], v[118:119] op_sel_hi:[1,0]
	v_pk_mul_f32 v[100:101], v[100:101], v[118:119] op_sel_hi:[1,0]
	v_pk_mul_f32 v[98:99], v[98:99], v[118:119] op_sel_hi:[1,0]
	v_pk_mul_f32 v[168:169], v[110:111], v[176:177] op_sel_hi:[1,0]
	v_pk_mul_f32 v[170:171], v[106:107], v[176:177] op_sel_hi:[1,0]
	v_pk_mul_f32 v[172:173], v[112:113], v[176:177] op_sel_hi:[1,0]
	v_pk_mul_f32 v[174:175], v[108:109], v[176:177] op_sel_hi:[1,0]
	v_exp_f32_e32 v168, v168
	v_exp_f32_e32 v169, v169
	v_exp_f32_e32 v170, v170
	v_exp_f32_e32 v171, v171
	v_exp_f32_e32 v172, v172
	v_exp_f32_e32 v173, v173
	v_exp_f32_e32 v174, v174
	v_exp_f32_e32 v175, v175
	v_pk_add_f32 v[168:169], v[168:169], 1.0 op_sel_hi:[1,0]
	v_pk_add_f32 v[170:171], v[170:171], 1.0 op_sel_hi:[1,0]
	v_pk_add_f32 v[172:173], v[172:173], 1.0 op_sel_hi:[1,0]
	v_pk_add_f32 v[174:175], v[174:175], 1.0 op_sel_hi:[1,0]
	v_rcp_f32_e32 v168, v168
	v_rcp_f32_e32 v169, v169
	v_rcp_f32_e32 v170, v170
	v_rcp_f32_e32 v171, v171
	v_rcp_f32_e32 v172, v172
	v_rcp_f32_e32 v173, v173
	v_rcp_f32_e32 v174, v174
	v_rcp_f32_e32 v175, v175
	v_pk_mul_f32 v[168:169], v[110:111], v[168:169]
	v_pk_mul_f32 v[170:171], v[106:107], v[170:171]
	v_pk_mul_f32 v[172:173], v[112:113], v[172:173]
	v_pk_mul_f32 v[174:175], v[108:109], v[174:175]
	v_pk_mul_f32 v[110:111], v[102:103], v[168:169]
	v_pk_mul_f32 v[106:107], v[98:99], v[170:171]
	v_pk_mul_f32 v[112:113], v[104:105], v[172:173]
	v_pk_mul_f32 v[108:109], v[100:101], v[174:175]
	v_add_u32_e32 v118, s83, v155
	v_cvt_pk_bf16_f32 v98, v110, v111
	v_cvt_pk_bf16_f32 v99, v112, v113
	v_cvt_pk_bf16_f32 v100, v106, v107
	v_mad_i64_i32 v[102:103], s[4:5], v118, s18, v[114:115]
	v_lshl_add_u64 v[102:103], v[102:103], 0, s[0:1]
	v_lshl_add_u64 v[102:103], v[102:103], 0, s[92:93]
	v_lshl_add_u64 v[102:103], v[102:103], 0, v[116:117]
	v_cvt_pk_bf16_f32 v101, v108, v109
	global_store_dwordx4 v[102:103], v[98:101], off nt
	s_nop 1
	v_pk_mul_f32 v[168:169], v[94:95], v[176:177] op_sel_hi:[1,0]
	v_pk_mul_f32 v[170:171], v[90:91], v[176:177] op_sel_hi:[1,0]
	v_pk_mul_f32 v[172:173], v[96:97], v[176:177] op_sel_hi:[1,0]
	v_pk_mul_f32 v[174:175], v[92:93], v[176:177] op_sel_hi:[1,0]
	v_exp_f32_e32 v168, v168
	v_exp_f32_e32 v169, v169
	v_exp_f32_e32 v170, v170
	v_exp_f32_e32 v171, v171
	v_exp_f32_e32 v172, v172
	v_exp_f32_e32 v173, v173
	v_exp_f32_e32 v174, v174
	v_exp_f32_e32 v175, v175
	v_pk_add_f32 v[168:169], v[168:169], 1.0 op_sel_hi:[1,0]
	v_pk_add_f32 v[170:171], v[170:171], 1.0 op_sel_hi:[1,0]
	v_pk_add_f32 v[172:173], v[172:173], 1.0 op_sel_hi:[1,0]
	v_pk_add_f32 v[174:175], v[174:175], 1.0 op_sel_hi:[1,0]
	v_rcp_f32_e32 v168, v168
	v_rcp_f32_e32 v169, v169
	v_rcp_f32_e32 v170, v170
	v_rcp_f32_e32 v171, v171
	v_rcp_f32_e32 v172, v172
	v_rcp_f32_e32 v173, v173
	v_rcp_f32_e32 v174, v174
	v_rcp_f32_e32 v175, v175
	v_pk_mul_f32 v[168:169], v[94:95], v[168:169]
	v_pk_mul_f32 v[170:171], v[90:91], v[170:171]
	v_pk_mul_f32 v[172:173], v[96:97], v[172:173]
	v_pk_mul_f32 v[174:175], v[92:93], v[174:175]
	v_pk_mul_f32 v[94:95], v[86:87], v[168:169]
	v_pk_mul_f32 v[90:91], v[82:83], v[170:171]
	v_pk_mul_f32 v[96:97], v[88:89], v[172:173]
	v_pk_mul_f32 v[92:93], v[84:85], v[174:175]
	v_add_u32_e32 v98, s91, v155
	v_cvt_pk_bf16_f32 v82, v94, v95
	v_cvt_pk_bf16_f32 v83, v96, v97
	v_cvt_pk_bf16_f32 v84, v90, v91
	v_mad_i64_i32 v[86:87], s[4:5], v98, s18, v[114:115]
	v_lshl_add_u64 v[86:87], v[86:87], 0, s[0:1]
	v_lshl_add_u64 v[86:87], v[86:87], 0, s[92:93]
	v_lshl_add_u64 v[86:87], v[86:87], 0, v[116:117]
	v_cvt_pk_bf16_f32 v85, v92, v93
	global_store_dwordx4 v[86:87], v[82:85], off nt
	s_nop 1
	v_mov_b32_e32 v82, v147
	v_pk_mul_f32 v[78:79], v[78:79], v[82:83] op_sel_hi:[1,0]
	v_pk_mul_f32 v[80:81], v[80:81], v[82:83] op_sel_hi:[1,0]
	v_pk_mul_f32 v[76:77], v[76:77], v[82:83] op_sel_hi:[1,0]
	v_pk_mul_f32 v[74:75], v[74:75], v[82:83] op_sel_hi:[1,0]
	v_pk_mul_f32 v[72:73], v[72:73], v[82:83] op_sel_hi:[1,0]
	v_pk_mul_f32 v[70:71], v[70:71], v[82:83] op_sel_hi:[1,0]
	v_pk_mul_f32 v[68:69], v[68:69], v[82:83] op_sel_hi:[1,0]
	v_pk_mul_f32 v[66:67], v[66:67], v[82:83] op_sel_hi:[1,0]
	v_pk_mul_f32 v[168:169], v[78:79], v[176:177] op_sel_hi:[1,0]
	v_pk_mul_f32 v[170:171], v[74:75], v[176:177] op_sel_hi:[1,0]
	v_pk_mul_f32 v[172:173], v[80:81], v[176:177] op_sel_hi:[1,0]
	v_pk_mul_f32 v[174:175], v[76:77], v[176:177] op_sel_hi:[1,0]
	v_exp_f32_e32 v168, v168
	v_exp_f32_e32 v169, v169
	v_exp_f32_e32 v170, v170
	v_exp_f32_e32 v171, v171
	v_exp_f32_e32 v172, v172
	v_exp_f32_e32 v173, v173
	v_exp_f32_e32 v174, v174
	v_exp_f32_e32 v175, v175
	v_pk_add_f32 v[168:169], v[168:169], 1.0 op_sel_hi:[1,0]
	v_pk_add_f32 v[170:171], v[170:171], 1.0 op_sel_hi:[1,0]
	v_pk_add_f32 v[172:173], v[172:173], 1.0 op_sel_hi:[1,0]
	v_pk_add_f32 v[174:175], v[174:175], 1.0 op_sel_hi:[1,0]
	v_rcp_f32_e32 v168, v168
	v_rcp_f32_e32 v169, v169
	v_rcp_f32_e32 v170, v170
	v_rcp_f32_e32 v171, v171
	v_rcp_f32_e32 v172, v172
	v_rcp_f32_e32 v173, v173
	v_rcp_f32_e32 v174, v174
	v_rcp_f32_e32 v175, v175
	v_pk_mul_f32 v[168:169], v[78:79], v[168:169]
	v_pk_mul_f32 v[170:171], v[74:75], v[170:171]
	v_pk_mul_f32 v[172:173], v[80:81], v[172:173]
	v_pk_mul_f32 v[174:175], v[76:77], v[174:175]
	v_pk_mul_f32 v[78:79], v[70:71], v[168:169]
	v_pk_mul_f32 v[74:75], v[66:67], v[170:171]
	v_pk_mul_f32 v[80:81], v[72:73], v[172:173]
	v_pk_mul_f32 v[76:77], v[68:69], v[174:175]
	v_add_u32_e32 v82, s51, v155
	v_cvt_pk_bf16_f32 v66, v78, v79
	v_cvt_pk_bf16_f32 v67, v80, v81
	v_cvt_pk_bf16_f32 v68, v74, v75
	v_mad_i64_i32 v[70:71], s[4:5], v82, s18, v[114:115]
	v_lshl_add_u64 v[70:71], v[70:71], 0, s[0:1]
	v_lshl_add_u64 v[70:71], v[70:71], 0, s[92:93]
	v_lshl_add_u64 v[70:71], v[70:71], 0, v[116:117]
	v_cvt_pk_bf16_f32 v69, v76, v77
	global_store_dwordx4 v[70:71], v[66:69], off nt
	s_nop 1
	v_pk_mul_f32 v[168:169], v[62:63], v[176:177] op_sel_hi:[1,0]
	v_pk_mul_f32 v[170:171], v[58:59], v[176:177] op_sel_hi:[1,0]
	v_pk_mul_f32 v[172:173], v[64:65], v[176:177] op_sel_hi:[1,0]
	v_pk_mul_f32 v[174:175], v[60:61], v[176:177] op_sel_hi:[1,0]
	v_exp_f32_e32 v168, v168
	v_exp_f32_e32 v169, v169
	v_exp_f32_e32 v170, v170
	v_exp_f32_e32 v171, v171
	v_exp_f32_e32 v172, v172
	v_exp_f32_e32 v173, v173
	v_exp_f32_e32 v174, v174
	v_exp_f32_e32 v175, v175
	v_pk_add_f32 v[168:169], v[168:169], 1.0 op_sel_hi:[1,0]
	v_pk_add_f32 v[170:171], v[170:171], 1.0 op_sel_hi:[1,0]
	v_pk_add_f32 v[172:173], v[172:173], 1.0 op_sel_hi:[1,0]
	v_pk_add_f32 v[174:175], v[174:175], 1.0 op_sel_hi:[1,0]
	v_rcp_f32_e32 v168, v168
	v_rcp_f32_e32 v169, v169
	v_rcp_f32_e32 v170, v170
	v_rcp_f32_e32 v171, v171
	v_rcp_f32_e32 v172, v172
	v_rcp_f32_e32 v173, v173
	v_rcp_f32_e32 v174, v174
	v_rcp_f32_e32 v175, v175
	v_pk_mul_f32 v[168:169], v[62:63], v[168:169]
	v_pk_mul_f32 v[170:171], v[58:59], v[170:171]
	v_pk_mul_f32 v[172:173], v[64:65], v[172:173]
	v_pk_mul_f32 v[174:175], v[60:61], v[174:175]
	v_pk_mul_f32 v[62:63], v[54:55], v[168:169]
	v_pk_mul_f32 v[58:59], v[50:51], v[170:171]
	v_pk_mul_f32 v[64:65], v[56:57], v[172:173]
	v_pk_mul_f32 v[60:61], v[52:53], v[174:175]
	v_add_u32_e32 v66, s88, v155
	v_cvt_pk_bf16_f32 v50, v62, v63
	v_cvt_pk_bf16_f32 v51, v64, v65
	v_cvt_pk_bf16_f32 v52, v58, v59
	v_mad_i64_i32 v[54:55], s[4:5], v66, s18, v[114:115]
	v_lshl_add_u64 v[54:55], v[54:55], 0, s[0:1]
	v_lshl_add_u64 v[54:55], v[54:55], 0, s[92:93]
	v_lshl_add_u64 v[54:55], v[54:55], 0, v[116:117]
	v_cvt_pk_bf16_f32 v53, v60, v61
	global_store_dwordx4 v[54:55], v[50:53], off nt
	s_nop 1
	v_mov_b32_e32 v50, v145
	v_pk_mul_f32 v[46:47], v[46:47], v[50:51] op_sel_hi:[1,0]
	v_pk_mul_f32 v[48:49], v[48:49], v[50:51] op_sel_hi:[1,0]
	v_pk_mul_f32 v[44:45], v[44:45], v[50:51] op_sel_hi:[1,0]
	v_pk_mul_f32 v[42:43], v[42:43], v[50:51] op_sel_hi:[1,0]
	v_pk_mul_f32 v[40:41], v[40:41], v[50:51] op_sel_hi:[1,0]
	v_pk_mul_f32 v[38:39], v[38:39], v[50:51] op_sel_hi:[1,0]
	v_pk_mul_f32 v[36:37], v[36:37], v[50:51] op_sel_hi:[1,0]
	v_pk_mul_f32 v[34:35], v[34:35], v[50:51] op_sel_hi:[1,0]
	v_pk_mul_f32 v[168:169], v[46:47], v[176:177] op_sel_hi:[1,0]
	v_pk_mul_f32 v[170:171], v[42:43], v[176:177] op_sel_hi:[1,0]
	v_pk_mul_f32 v[172:173], v[48:49], v[176:177] op_sel_hi:[1,0]
	v_pk_mul_f32 v[174:175], v[44:45], v[176:177] op_sel_hi:[1,0]
	v_exp_f32_e32 v168, v168
	v_exp_f32_e32 v169, v169
	v_exp_f32_e32 v170, v170
	v_exp_f32_e32 v171, v171
	v_exp_f32_e32 v172, v172
	v_exp_f32_e32 v173, v173
	v_exp_f32_e32 v174, v174
	v_exp_f32_e32 v175, v175
	v_pk_add_f32 v[168:169], v[168:169], 1.0 op_sel_hi:[1,0]
	v_pk_add_f32 v[170:171], v[170:171], 1.0 op_sel_hi:[1,0]
	v_pk_add_f32 v[172:173], v[172:173], 1.0 op_sel_hi:[1,0]
	v_pk_add_f32 v[174:175], v[174:175], 1.0 op_sel_hi:[1,0]
	v_rcp_f32_e32 v168, v168
	v_rcp_f32_e32 v169, v169
	v_rcp_f32_e32 v170, v170
	v_rcp_f32_e32 v171, v171
	v_rcp_f32_e32 v172, v172
	v_rcp_f32_e32 v173, v173
	v_rcp_f32_e32 v174, v174
	v_rcp_f32_e32 v175, v175
	v_pk_mul_f32 v[168:169], v[46:47], v[168:169]
	v_pk_mul_f32 v[170:171], v[42:43], v[170:171]
	v_pk_mul_f32 v[172:173], v[48:49], v[172:173]
	v_pk_mul_f32 v[174:175], v[44:45], v[174:175]
	v_pk_mul_f32 v[46:47], v[38:39], v[168:169]
	v_pk_mul_f32 v[42:43], v[34:35], v[170:171]
	v_pk_mul_f32 v[48:49], v[40:41], v[172:173]
	v_pk_mul_f32 v[44:45], v[36:37], v[174:175]
	v_add_u32_e32 v50, s60, v155
	v_cvt_pk_bf16_f32 v34, v46, v47
	v_cvt_pk_bf16_f32 v35, v48, v49
	v_cvt_pk_bf16_f32 v36, v42, v43
	v_mad_i64_i32 v[38:39], s[4:5], v50, s18, v[114:115]
	v_lshl_add_u64 v[38:39], v[38:39], 0, s[0:1]
	v_lshl_add_u64 v[38:39], v[38:39], 0, s[92:93]
	v_lshl_add_u64 v[38:39], v[38:39], 0, v[116:117]
	v_cvt_pk_bf16_f32 v37, v44, v45
	global_store_dwordx4 v[38:39], v[34:37], off nt
	s_nop 1
	v_pk_mul_f32 v[168:169], v[30:31], v[176:177] op_sel_hi:[1,0]
	v_pk_mul_f32 v[170:171], v[26:27], v[176:177] op_sel_hi:[1,0]
	v_pk_mul_f32 v[172:173], v[32:33], v[176:177] op_sel_hi:[1,0]
	v_pk_mul_f32 v[174:175], v[28:29], v[176:177] op_sel_hi:[1,0]
	v_exp_f32_e32 v168, v168
	v_exp_f32_e32 v169, v169
	v_exp_f32_e32 v170, v170
	v_exp_f32_e32 v171, v171
	v_exp_f32_e32 v172, v172
	v_exp_f32_e32 v173, v173
	v_exp_f32_e32 v174, v174
	v_exp_f32_e32 v175, v175
	v_pk_add_f32 v[168:169], v[168:169], 1.0 op_sel_hi:[1,0]
	v_pk_add_f32 v[170:171], v[170:171], 1.0 op_sel_hi:[1,0]
	v_pk_add_f32 v[172:173], v[172:173], 1.0 op_sel_hi:[1,0]
	v_pk_add_f32 v[174:175], v[174:175], 1.0 op_sel_hi:[1,0]
	v_rcp_f32_e32 v168, v168
	v_rcp_f32_e32 v169, v169
	v_rcp_f32_e32 v170, v170
	v_rcp_f32_e32 v171, v171
	v_rcp_f32_e32 v172, v172
	v_rcp_f32_e32 v173, v173
	v_rcp_f32_e32 v174, v174
	v_rcp_f32_e32 v175, v175
	v_pk_mul_f32 v[168:169], v[30:31], v[168:169]
	v_pk_mul_f32 v[170:171], v[26:27], v[170:171]
	v_pk_mul_f32 v[172:173], v[32:33], v[172:173]
	v_pk_mul_f32 v[174:175], v[28:29], v[174:175]
	v_pk_mul_f32 v[30:31], v[22:23], v[168:169]
	v_pk_mul_f32 v[26:27], v[18:19], v[170:171]
	v_pk_mul_f32 v[32:33], v[24:25], v[172:173]
	v_pk_mul_f32 v[28:29], v[20:21], v[174:175]
	v_add_u32_e32 v34, s61, v155
	v_cvt_pk_bf16_f32 v18, v30, v31
	v_cvt_pk_bf16_f32 v19, v32, v33
	v_cvt_pk_bf16_f32 v20, v26, v27
	v_mad_i64_i32 v[22:23], s[4:5], v34, s18, v[114:115]
	v_lshl_add_u64 v[22:23], v[22:23], 0, s[0:1]
	v_lshl_add_u64 v[22:23], v[22:23], 0, s[92:93]
	v_lshl_add_u64 v[22:23], v[22:23], 0, v[116:117]
	v_cvt_pk_bf16_f32 v21, v28, v29
	global_store_dwordx4 v[22:23], v[18:21], off nt
	s_nop 1
	v_mov_b32_e32 v18, v143
	v_pk_mul_f32 v[14:15], v[14:15], v[18:19] op_sel_hi:[1,0]
	v_pk_mul_f32 v[16:17], v[16:17], v[18:19] op_sel_hi:[1,0]
	v_pk_mul_f32 v[12:13], v[12:13], v[18:19] op_sel_hi:[1,0]
	v_pk_mul_f32 v[10:11], v[10:11], v[18:19] op_sel_hi:[1,0]
	v_pk_mul_f32 v[8:9], v[8:9], v[18:19] op_sel_hi:[1,0]
	v_pk_mul_f32 v[6:7], v[6:7], v[18:19] op_sel_hi:[1,0]
	v_pk_mul_f32 v[4:5], v[4:5], v[18:19] op_sel_hi:[1,0]
	v_pk_mul_f32 v[2:3], v[2:3], v[18:19] op_sel_hi:[1,0]
	v_pk_mul_f32 v[168:169], v[14:15], v[176:177] op_sel_hi:[1,0]
	v_pk_mul_f32 v[170:171], v[10:11], v[176:177] op_sel_hi:[1,0]
	v_pk_mul_f32 v[172:173], v[16:17], v[176:177] op_sel_hi:[1,0]
	v_pk_mul_f32 v[174:175], v[12:13], v[176:177] op_sel_hi:[1,0]
	v_exp_f32_e32 v168, v168
	v_exp_f32_e32 v169, v169
	v_exp_f32_e32 v170, v170
	v_exp_f32_e32 v171, v171
	v_exp_f32_e32 v172, v172
	v_exp_f32_e32 v173, v173
	v_exp_f32_e32 v174, v174
	v_exp_f32_e32 v175, v175
	v_pk_add_f32 v[168:169], v[168:169], 1.0 op_sel_hi:[1,0]
	v_pk_add_f32 v[170:171], v[170:171], 1.0 op_sel_hi:[1,0]
	v_pk_add_f32 v[172:173], v[172:173], 1.0 op_sel_hi:[1,0]
	v_pk_add_f32 v[174:175], v[174:175], 1.0 op_sel_hi:[1,0]
	v_rcp_f32_e32 v168, v168
	v_rcp_f32_e32 v169, v169
	v_rcp_f32_e32 v170, v170
	v_rcp_f32_e32 v171, v171
	v_rcp_f32_e32 v172, v172
	v_rcp_f32_e32 v173, v173
	v_rcp_f32_e32 v174, v174
	v_rcp_f32_e32 v175, v175
	v_pk_mul_f32 v[168:169], v[14:15], v[168:169]
	v_pk_mul_f32 v[170:171], v[10:11], v[170:171]
	v_pk_mul_f32 v[172:173], v[16:17], v[172:173]
	v_pk_mul_f32 v[174:175], v[12:13], v[174:175]
	v_pk_mul_f32 v[14:15], v[6:7], v[168:169]
	v_pk_mul_f32 v[10:11], v[2:3], v[170:171]
	v_pk_mul_f32 v[16:17], v[8:9], v[172:173]
	v_pk_mul_f32 v[12:13], v[4:5], v[174:175]
	v_add_u32_e32 v18, s62, v155
	v_cvt_pk_bf16_f32 v2, v14, v15
	v_cvt_pk_bf16_f32 v3, v16, v17
	v_cvt_pk_bf16_f32 v4, v10, v11
	v_mad_i64_i32 v[6:7], s[4:5], v18, s18, v[114:115]
	v_lshl_add_u64 v[6:7], v[6:7], 0, s[0:1]
	v_lshl_add_u64 v[6:7], v[6:7], 0, s[92:93]
	v_lshl_add_u64 v[6:7], v[6:7], 0, v[116:117]
	s_mov_b64 s[4:5], s[12:13]
	s_mov_b64 s[0:1], s[10:11]
	v_cvt_pk_bf16_f32 v5, v12, v13
	global_store_dwordx4 v[6:7], v[2:5], off nt
	s_cbranch_vccnz .LBB0_669
